# P0 K-cache f32->bf16 conversion rewritten by hand: all 6 loads per thread in flight before one wait (was load->wait->store per element)
# baseline (speedup 1.0000x reference)
.LBB0_148:
	s_ashr_i32 s3, s2, 31
	s_ashr_i32 s49, s48, 31
	s_load_dwordx2 s[14:15], s[0:1], 0x10
	s_load_dwordx2 s[16:17], s[0:1], 0x20
	s_lshl_b32 s4, s2, 9
	v_add_u32_e32 v0, s4, v4
	s_lshl_b32 s4, s48, 9
	s_add_u32 s12, s52, 0x1448000
	s_addc_u32 s13, s53, 0
	s_add_u32 s18, s52, 0x1848000
	s_addc_u32 s19, s53, 0
	s_mov_b32 s8, 0x40000
	s_mov_b32 s9, 0x80000
	s_mov_b64 s[10:11], exec
	v_cmp_gt_u32_e32 vcc, s9, v0
	s_and_b64 exec, exec, vcc
	s_cbranch_execz .LBB0_166
	s_waitcnt lgkmcnt(0)
.Lkc_loop:
	s_mov_b64 s[20:21], exec
	v_add_u32_e32 v1, s4, v0
	v_add_u32_e32 v2, s4, v1
	v_add_u32_e32 v3, s4, v2
	v_cmp_gt_u32_e64 s[22:23], s9, v0
	v_cmp_gt_u32_e64 s[30:31], s8, v0
	v_cmp_gt_u32_e64 s[24:25], s9, v1
	v_cmp_gt_u32_e64 s[34:35], s8, v1
	v_cmp_gt_u32_e64 s[26:27], s9, v2
	v_cmp_gt_u32_e64 s[36:37], s8, v2
	v_cmp_gt_u32_e64 s[28:29], s9, v3
	v_cmp_gt_u32_e64 s[38:39], s8, v3
	s_and_b64 exec, s[20:21], s[22:23]
	v_bfe_u32 v5, v0, 15, 3
	v_lshlrev_b32_e32 v5, 20, v5
	v_bfe_u32 v6, v0, 18, 1
	v_lshl_or_b32 v5, v6, 19, v5
	v_bfe_u32 v6, v0, 4, 9
	v_lshl_or_b32 v5, v6, 10, v5
	v_bfe_u32 v6, v0, 13, 2
	v_lshl_or_b32 v5, v6, 8, v5
	v_and_b32_e32 v6, 15, v0
	v_lshl_or_b32 v5, v6, 4, v5
	global_load_dwordx4 v[210:213], v5, s[16:17] nt
	s_and_b64 exec, exec, s[30:31]
	v_bfe_u32 v7, v0, 14, 3
	v_lshlrev_b32_e32 v7, 19, v7
	v_bfe_u32 v8, v0, 17, 1
	v_lshl_or_b32 v7, v8, 18, v7
	v_bfe_u32 v8, v0, 4, 9
	v_lshl_or_b32 v7, v8, 9, v7
	v_bfe_u32 v8, v0, 13, 1
	v_lshl_or_b32 v7, v8, 8, v7
	v_and_b32_e32 v8, 15, v0
	v_lshl_or_b32 v7, v8, 4, v7
	global_load_dwordx4 v[226:229], v7, s[14:15] nt
	s_and_b64 exec, s[20:21], s[24:25]
	v_bfe_u32 v5, v1, 15, 3
	v_lshlrev_b32_e32 v5, 20, v5
	v_bfe_u32 v6, v1, 18, 1
	v_lshl_or_b32 v5, v6, 19, v5
	v_bfe_u32 v6, v1, 4, 9
	v_lshl_or_b32 v5, v6, 10, v5
	v_bfe_u32 v6, v1, 13, 2
	v_lshl_or_b32 v5, v6, 8, v5
	v_and_b32_e32 v6, 15, v1
	v_lshl_or_b32 v5, v6, 4, v5
	global_load_dwordx4 v[214:217], v5, s[16:17] nt
	s_and_b64 exec, exec, s[34:35]
	v_bfe_u32 v7, v1, 14, 3
	v_lshlrev_b32_e32 v7, 19, v7
	v_bfe_u32 v8, v1, 17, 1
	v_lshl_or_b32 v7, v8, 18, v7
	v_bfe_u32 v8, v1, 4, 9
	v_lshl_or_b32 v7, v8, 9, v7
	v_bfe_u32 v8, v1, 13, 1
	v_lshl_or_b32 v7, v8, 8, v7
	v_and_b32_e32 v8, 15, v1
	v_lshl_or_b32 v7, v8, 4, v7
	global_load_dwordx4 v[230:233], v7, s[14:15] nt
	s_and_b64 exec, s[20:21], s[26:27]
	v_bfe_u32 v5, v2, 15, 3
	v_lshlrev_b32_e32 v5, 20, v5
	v_bfe_u32 v6, v2, 18, 1
	v_lshl_or_b32 v5, v6, 19, v5
	v_bfe_u32 v6, v2, 4, 9
	v_lshl_or_b32 v5, v6, 10, v5
	v_bfe_u32 v6, v2, 13, 2
	v_lshl_or_b32 v5, v6, 8, v5
	v_and_b32_e32 v6, 15, v2
	v_lshl_or_b32 v5, v6, 4, v5
	global_load_dwordx4 v[218:221], v5, s[16:17] nt
	s_and_b64 exec, exec, s[36:37]
	v_bfe_u32 v7, v2, 14, 3
	v_lshlrev_b32_e32 v7, 19, v7
	v_bfe_u32 v8, v2, 17, 1
	v_lshl_or_b32 v7, v8, 18, v7
	v_bfe_u32 v8, v2, 4, 9
	v_lshl_or_b32 v7, v8, 9, v7
	v_bfe_u32 v8, v2, 13, 1
	v_lshl_or_b32 v7, v8, 8, v7
	v_and_b32_e32 v8, 15, v2
	v_lshl_or_b32 v7, v8, 4, v7
	global_load_dwordx4 v[234:237], v7, s[14:15] nt
	s_and_b64 exec, s[20:21], s[28:29]
	v_bfe_u32 v5, v3, 15, 3
	v_lshlrev_b32_e32 v5, 20, v5
	v_bfe_u32 v6, v3, 18, 1
	v_lshl_or_b32 v5, v6, 19, v5
	v_bfe_u32 v6, v3, 4, 9
	v_lshl_or_b32 v5, v6, 10, v5
	v_bfe_u32 v6, v3, 13, 2
	v_lshl_or_b32 v5, v6, 8, v5
	v_and_b32_e32 v6, 15, v3
	v_lshl_or_b32 v5, v6, 4, v5
	global_load_dwordx4 v[222:225], v5, s[16:17] nt
	s_and_b64 exec, exec, s[38:39]
	v_bfe_u32 v7, v3, 14, 3
	v_lshlrev_b32_e32 v7, 19, v7
	v_bfe_u32 v8, v3, 17, 1
	v_lshl_or_b32 v7, v8, 18, v7
	v_bfe_u32 v8, v3, 4, 9
	v_lshl_or_b32 v7, v8, 9, v7
	v_bfe_u32 v8, v3, 13, 1
	v_lshl_or_b32 v7, v8, 8, v7
	v_and_b32_e32 v8, 15, v3
	v_lshl_or_b32 v7, v8, 4, v7
	global_load_dwordx4 v[242:245], v7, s[14:15] nt
	s_waitcnt vmcnt(0)
	s_and_b64 exec, s[20:21], s[22:23]
	v_lshlrev_b32_e32 v5, 3, v0
	v_cvt_pk_bf16_f32 v210, v210, v211
	v_cvt_pk_bf16_f32 v211, v212, v213
	global_store_dwordx2 v5, v[210:211], s[18:19]
	s_and_b64 exec, exec, s[30:31]
	v_cvt_pk_bf16_f32 v226, v226, v227
	v_cvt_pk_bf16_f32 v227, v228, v229
	global_store_dwordx2 v5, v[226:227], s[12:13]
	s_and_b64 exec, s[20:21], s[24:25]
	v_lshlrev_b32_e32 v7, 3, v1
	v_cvt_pk_bf16_f32 v214, v214, v215
	v_cvt_pk_bf16_f32 v215, v216, v217
	global_store_dwordx2 v7, v[214:215], s[18:19]
	s_and_b64 exec, exec, s[34:35]
	v_cvt_pk_bf16_f32 v230, v230, v231
	v_cvt_pk_bf16_f32 v231, v232, v233
	global_store_dwordx2 v7, v[230:231], s[12:13]
	s_and_b64 exec, s[20:21], s[26:27]
	v_lshlrev_b32_e32 v5, 3, v2
	v_cvt_pk_bf16_f32 v218, v218, v219
	v_cvt_pk_bf16_f32 v219, v220, v221
	global_store_dwordx2 v5, v[218:219], s[18:19]
	s_and_b64 exec, exec, s[36:37]
	v_cvt_pk_bf16_f32 v234, v234, v235
	v_cvt_pk_bf16_f32 v235, v236, v237
	global_store_dwordx2 v5, v[234:235], s[12:13]
	s_and_b64 exec, s[20:21], s[28:29]
	v_lshlrev_b32_e32 v7, 3, v3
	v_cvt_pk_bf16_f32 v222, v222, v223
	v_cvt_pk_bf16_f32 v223, v224, v225
	global_store_dwordx2 v7, v[222:223], s[18:19]
	s_and_b64 exec, exec, s[38:39]
	v_cvt_pk_bf16_f32 v242, v242, v243
	v_cvt_pk_bf16_f32 v243, v244, v245
	global_store_dwordx2 v7, v[242:243], s[12:13]
	s_mov_b64 exec, s[20:21]
	v_add_u32_e32 v0, s4, v3
	v_cmp_gt_u32_e32 vcc, s9, v0
	s_and_b64 exec, exec, vcc
	s_cbranch_execnz .Lkc_loop
